# grid barrier: workgroups 0..7 (one per XCD) issue an un-waited buffer_wbl2 at their own arrival so the XCD leader's writeback finds the L2 mostly clean
# baseline (speedup 1.0000x reference)
; __device__ __forceinline__ unsigned xb_ld(unsigned* p)              { return __hip_atomic_load(p, __ATOMIC_RELAXED, __HIP_MEMORY_SCOPE_AGENT); }
; __device__ __forceinline__ unsigned xb_add(unsigned* p, unsigned v) { return __hip_atomic_fetch_add(p, v, __ATOMIC_RELAXED, __HIP_MEMORY_SCOPE_AGENT); }
; #define XB_SPIN(cond, bar) do { unsigned _sp = 0; while (cond) { __builtin_amdgcn_s_sleep(1); \
;     if ((++_sp & 255u) == 0u) { if (xb_ld(&(bar)[XB_TMO])) break; if (_sp > XB_SPIN_CAP) { atomicAdd(&(bar)[XB_TMO], 1u); break; } } } } while (0)
; __device__ __forceinline__ void xcd_barrier(const XcdBarrier& b) {
;     ...
;         const unsigned old = xb_add(&bar[XB_XSUB(b.x)], 1u);
;         const unsigned gen = old / nloc;
;         if (old + 1u == (gen + 1u) * nloc) {
;             __builtin_amdgcn_fence(__ATOMIC_RELEASE, "agent");
;             asm volatile("s_waitcnt vmcnt(0)" ::: "memory");
;             const unsigned og = xb_add(&bar[XB_TOP], 1u);
;             const unsigned tg = og / nx;
;             if (og + 1u == (tg + 1u) * nx) xb_add(&bar[XB_TOPGEN], 1u);
;             else XB_SPIN(xb_ld(&bar[XB_TOPGEN]) == tg, bar);
;             __builtin_amdgcn_fence(__ATOMIC_ACQUIRE, "agent");
;             xb_add(&bar[XB_XGEN(b.x)], 1u);
;             asm volatile("s_waitcnt vmcnt(0)" ::: "memory");
;         } else {
;             XB_SPIN(xb_ld(&bar[XB_XGEN(b.x)]) == gen, bar);
.LBB0_32:
	v_readlane_b32 s2, v253, 35
	v_readlane_b32 s4, v253, 36
	s_lshl_b32 s2, s2, 6
	v_readlane_b32 s5, v253, 37
	s_mov_b32 s3, s4
	s_lshl_b64 s[2:3], s[2:3], 2
	v_readlane_b32 s4, v252, 15
	v_readlane_b32 s5, v252, 16
	s_add_u32 s2, s4, s2
	s_addc_u32 s3, s5, s3
	v_mov_b32_e32 v1, 0x1000
	v_readlane_b32 s21, v252, 0
	s_cmp_lt_u32 s21, 8
	s_cbranch_scc0 .Lbar_noflush
	buffer_wbl2 sc1
.Lbar_noflush:
	global_atomic_add v3, v1, v232, s[2:3] offset:1024 sc0
	v_cvt_f32_u32_e32 v1, v2
	v_sub_u32_e32 v4, 0, v2
	v_rcp_iflag_f32_e32 v1, v1
	s_nop 0
	v_mul_f32_e32 v1, 0x4f7ffffe, v1
	v_cvt_u32_f32_e32 v1, v1
	v_mul_lo_u32 v4, v4, v1
	v_mul_hi_u32 v4, v1, v4
	v_add_u32_e32 v1, v1, v4
	s_waitcnt vmcnt(0)
	v_mul_hi_u32 v1, v3, v1
	v_mul_lo_u32 v4, v1, v2
	v_sub_u32_e32 v4, v3, v4
	v_add_u32_e32 v5, 1, v1
	v_cmp_ge_u32_e32 vcc, v4, v2
	v_add_u32_e32 v3, 1, v3
	s_nop 0
	v_cndmask_b32_e32 v1, v1, v5, vcc
	v_sub_u32_e32 v5, v4, v2
	v_cndmask_b32_e32 v4, v4, v5, vcc
	v_add_u32_e32 v5, 1, v1
	v_cmp_ge_u32_e32 vcc, v4, v2
	s_nop 1
	v_cndmask_b32_e32 v1, v1, v5, vcc
	v_mul_lo_u32 v4, v2, v1
	v_add_u32_e32 v2, v4, v2
	v_cmp_ne_u32_e32 vcc, v3, v2
	s_and_saveexec_b64 s[4:5], vcc
	s_xor_b64 s[4:5], exec, s[4:5]
	s_cbranch_execz .LBB0_46
	s_waitcnt lgkmcnt(0)
	v_mov_b32_e32 v0, 0x2000
	global_load_dword v0, v0, s[2:3] offset:1024 sc1
	s_add_u32 s8, s2, 0x2400
	s_addc_u32 s9, s3, 0
	s_waitcnt vmcnt(0)
	v_cmp_eq_u32_e32 vcc, v0, v1
	s_and_saveexec_b64 s[6:7], vcc
	s_cbranch_execz .LBB0_45
	s_mov_b32 s20, 1
	s_mov_b64 s[10:11], 0
	s_branch .LBB0_36
